# projection epilogue: the leading half issues its rstd loads before the align barrier
# baseline (speedup 1.0000x reference)
; #define PG8_BAR __builtin_amdgcn_s_barrier()
; template <int K>
; __device__ __forceinline__ void epilogue_p(const f32x4 (&acc)[2][2][4][2], const Unit& u, const EpiDesc& E, const Ctx& C, int wr, int wc, int fr, int fq) {
;     const int row0 = u.pm * 256 + wr * 64 + fr;
;     const int lc8 = 32 * wc + 8 * fq;
;     if (K == EK_SWIGLU || K == EK_PROJ) {
;         float rstd[2][4];
; #pragma unroll
;         for (int ai = 0; ai < 2; ++ai)
; #pragma unroll
;             for (int m = 0; m < 4; ++m) rstd[ai][m] = E.rss_in[row0 + 128 * ai + 16 * m];
; template <bool PERM>
; __device__ __forceinline__ void gemm_phase(LAS unsigned char* lds, const Gemm g, const Sched& S, const EpiDesc& E, const Ctx& C) {
;     ...
;         if (wr == 0) PG8_BAR;
.LBB0_64:
	s_cmp_eq_u32 s24, 2
	s_cbranch_scc0 .Lpj_bar
	s_lshl_b32 s61, s18, 8
	s_add_i32 s61, s61, s74
	v_or_b32_e32 v192, s61, v177
	v_ashrrev_i32_e32 v193, 31, v192
	v_lshl_add_u64 v[130:131], v[192:193], 2, s[12:13]
	global_load_dword v0, v[130:131], off
	global_load_dword v132, v[130:131], off offset:64
	global_load_dword v133, v[130:131], off offset:128
	global_load_dword v134, v[130:131], off offset:192
	global_load_dword v135, v[130:131], off offset:512
	global_load_dword v136, v[130:131], off offset:576
	global_load_dword v137, v[130:131], off offset:640
	s_nop 0
	global_load_dword v130, v[130:131], off offset:704
	s_barrier
	s_branch .Lpj_loaded

; __device__ __forceinline__ float sigmoidf_(float v) { return __builtin_amdgcn_rcpf(1.f + __builtin_amdgcn_exp2f(-1.4426950408889634f * v)); }
; __device__ __forceinline__ u32x4 pk8(f32x4 a, f32x4 b) { const u32x2 p = pk4(a), q = pk4(b); return (u32x4){p.x, p.y, q.x, q.y}; }
; template <int K>
; __device__ __forceinline__ void epilogue_p(const f32x4 (&acc)[2][2][4][2], const Unit& u, const EpiDesc& E, const Ctx& C, int wr, int wc, int fr, int fq) {
;     ...
;         for (int ai = 0; ai < 2; ++ai)
; #pragma unroll
;             for (int m = 0; m < 4; ++m) rstd[ai][m] = __builtin_amdgcn_rsqf(rstd[ai][m] * (1.f / 1024.f) + RMS_EPS);
;     ...
;             } else {
;                 const int br = (pn - 10) >> 2, cb = 256 * ((pn - 10) & 3);
; #pragma unroll
;                 for (int ai = 0; ai < 2; ++ai)
; #pragma unroll
;                     for (int m = 0; m < 4; ++m) {
;                         const int row = row0 + 128 * ai + 16 * m;
; #pragma unroll
;                         for (int bj = 0; bj < 2; ++bj) {
;                             f32x4 sg[2];
; #pragma unroll
;                             for (int n = 0; n < 2; ++n) {
;                                 const f32x4 x = acc[ai][bj][m][n] * rstd[ai][m];
; #pragma unroll
;                                 for (int i = 0; i < 4; ++i) sg[n][i] = fmaxf(sigmoidf_(x[i]), 1e-30f);
;                             }
;                             *(u32x4*)(C.G + (size_t)row * 3072 + br * 1024 + cb + 128 * bj + lc8) = pk8(sg[0], sg[1]);
;                         }
;                     }
.Lpj_loaded:
	v_or_b32_e32 v190, 16, v192
	v_or_b32_e32 v186, 32, v192
	v_or_b32_e32 v164, 48, v192
	v_add_u32_e32 v160, 0x80, v192
	v_add_u32_e32 v156, 0x90, v192
	v_add_u32_e32 v152, 0xa0, v192
	v_add_u32_e32 v148, 0xb0, v192
	v_ashrrev_i32_e32 v191, 31, v190
	v_ashrrev_i32_e32 v187, 31, v186
	v_ashrrev_i32_e32 v165, 31, v164
	v_ashrrev_i32_e32 v161, 31, v160
	v_ashrrev_i32_e32 v157, 31, v156
	v_ashrrev_i32_e32 v153, 31, v152
	v_ashrrev_i32_e32 v149, 31, v148
	s_cmp_gt_i32 s87, 3
	s_mov_b64 s[2:3], -1
	s_waitcnt vmcnt(0)
	v_fmamk_f32 v0, v0, 0x3a800000, v231
	v_fmamk_f32 v131, v132, 0x3a800000, v231
	v_fmamk_f32 v132, v133, 0x3a800000, v231
	v_fmamk_f32 v133, v134, 0x3a800000, v231
	v_fmamk_f32 v134, v135, 0x3a800000, v231
	v_fmamk_f32 v135, v136, 0x3a800000, v231
	v_fmamk_f32 v136, v137, 0x3a800000, v231
	v_fmamk_f32 v130, v130, 0x3a800000, v231
	v_rsq_f32_e32 v194, v0
	v_rsq_f32_e32 v188, v131
	v_rsq_f32_e32 v184, v132
	v_rsq_f32_e32 v162, v133
	v_rsq_f32_e32 v158, v134
	v_rsq_f32_e32 v154, v135
	v_rsq_f32_e32 v150, v136
	v_rsq_f32_e32 v146, v130
	s_cbranch_scc0 .LBB0_211
	s_cmp_gt_u32 s87, 7
	s_cbranch_scc0 .LBB0_145
	s_lshl_b32 s20, s87, 8
	s_cmp_gt_u32 s87, 9
	s_cbranch_scc0 .LBB0_110
	v_mul_f32_e32 v132, v129, v194
	v_mul_f32_e32 v132, 0xbfb8aa3b, v132
	v_exp_f32_e32 v132, v132
	v_mul_f32_e32 v133, v122, v194
	v_mul_f32_e32 v134, v123, v194
	v_mul_f32_e32 v133, 0xbfb8aa3b, v133
	v_add_f32_e32 v132, 1.0, v132
	v_mul_f32_e32 v134, 0xbfb8aa3b, v134
	v_rcp_f32_e32 v132, v132
	v_exp_f32_e32 v133, v133
	v_exp_f32_e32 v134, v134
	v_mul_f32_e32 v130, v127, v194
	v_mul_f32_e32 v131, v128, v194
	v_mul_f32_e32 v0, v126, v194
	v_mul_f32_e32 v130, 0xbfb8aa3b, v130
	v_mul_f32_e32 v131, 0xbfb8aa3b, v131
	v_mul_f32_e32 v136, v125, v194
	v_mul_f32_e32 v0, 0xbfb8aa3b, v0
	v_exp_f32_e32 v130, v130
	v_exp_f32_e32 v131, v131
	v_max_f32_e32 v135, 0xda24260, v132
	v_add_f32_e32 v132, 1.0, v133
	v_add_f32_e32 v133, 1.0, v134
	v_mul_f32_e32 v134, v124, v194
	v_mul_f32_e32 v136, 0xbfb8aa3b, v136
	v_exp_f32_e32 v0, v0
	v_mul_f32_e32 v134, 0xbfb8aa3b, v134
	v_exp_f32_e32 v136, v136
	v_exp_f32_e32 v134, v134
	v_add_f32_e32 v130, 1.0, v130
	v_add_f32_e32 v131, 1.0, v131
	v_add_f32_e32 v0, 1.0, v0
	v_rcp_f32_e32 v130, v130
	v_rcp_f32_e32 v131, v131
	v_add_f32_e32 v136, 1.0, v136
	v_rcp_f32_e32 v0, v0
	v_rcp_f32_e32 v132, v132
	v_rcp_f32_e32 v133, v133
	v_add_f32_e32 v134, 1.0, v134
	v_rcp_f32_e32 v136, v136
	s_add_i32 s2, s20, 0xfffff600
	v_rcp_f32_e32 v134, v134
	s_and_b32 s21, s2, 0x300
	s_and_b32 s18, s2, 0x7ffffc00
	v_readlane_b32 s2, v254, 31
	v_max_f32_e32 v130, 0xda24260, v130
	v_max_f32_e32 v131, 0xda24260, v131
	v_readlane_b32 s3, v254, 32
	v_max_f32_e32 v0, 0xda24260, v0
	v_max_f32_e32 v137, 0xda24260, v132
	v_max_f32_e32 v138, 0xda24260, v133
	v_max_f32_e32 v136, 0xda24260, v136
	v_cvt_pk_bf16_f32 v132, v0, v130
	v_cvt_pk_bf16_f32 v133, v131, v135
	v_mov_b64_e32 v[130:131], s[2:3]
	v_max_f32_e32 v139, 0xda24260, v134
	v_cvt_pk_bf16_f32 v134, v137, v138
	v_cvt_pk_bf16_f32 v135, v139, v136
	v_mad_i64_i32 v[136:137], s[2:3], v192, s44, v[130:131]
	s_lshl_b32 s18, s18, 1
	v_mul_f32_e32 v0, v118, v194
	v_lshl_add_u64 v[136:137], v[136:137], 0, s[18:19]
	s_lshl_b32 s2, s21, 1
	s_mov_b32 s3, s19
	v_mul_f32_e32 v0, 0xbfb8aa3b, v0
	v_lshl_add_u64 v[136:137], v[136:137], 0, s[2:3]
	v_exp_f32_e32 v138, v0
	v_lshlrev_b32_e32 v0, 1, v178
	v_lshl_add_u64 v[136:137], v[136:137], 0, v[0:1]
	global_store_dwordx4 v[136:137], v[132:135], off
	v_mul_f32_e32 v139, v115, v194
	v_mul_f32_e32 v139, 0xbfb8aa3b, v139
	v_mul_f32_e32 v133, v119, v194
	v_mul_f32_e32 v134, v120, v194
	v_mul_f32_e32 v133, 0xbfb8aa3b, v133
	v_mul_f32_e32 v134, 0xbfb8aa3b, v134
	v_mul_f32_e32 v135, v121, v194
	v_exp_f32_e32 v133, v133
	v_exp_f32_e32 v134, v134
	v_mul_f32_e32 v135, 0xbfb8aa3b, v135
	v_add_f32_e32 v132, 1.0, v138
	v_exp_f32_e32 v135, v135
	v_mul_f32_e32 v138, v114, v194
	v_mul_f32_e32 v138, 0xbfb8aa3b, v138
	v_mul_f32_e32 v140, v116, v194
	v_mul_f32_e32 v141, v117, v194
	v_exp_f32_e32 v138, v138
	v_exp_f32_e32 v139, v139
	v_mul_f32_e32 v140, 0xbfb8aa3b, v140
	v_mul_f32_e32 v141, 0xbfb8aa3b, v141
	v_add_f32_e32 v133, 1.0, v133
	v_add_f32_e32 v134, 1.0, v134
	v_exp_f32_e32 v140, v140
	v_exp_f32_e32 v141, v141
	v_rcp_f32_e32 v132, v132
	v_rcp_f32_e32 v133, v133
	v_rcp_f32_e32 v134, v134
	v_add_f32_e32 v135, 1.0, v135
	v_rcp_f32_e32 v135, v135
	v_add_f32_e32 v138, 1.0, v138
	v_add_f32_e32 v139, 1.0, v139
	v_rcp_f32_e32 v138, v138
	v_rcp_f32_e32 v139, v139
	v_add_f32_e32 v140, 1.0, v140
	v_add_f32_e32 v141, 1.0, v141
	v_max_f32_e32 v132, 0xda24260, v132
	v_max_f32_e32 v133, 0xda24260, v133
	v_max_f32_e32 v134, 0xda24260, v134
	v_rcp_f32_e32 v140, v140
	v_rcp_f32_e32 v141, v141
	v_max_f32_e32 v135, 0xda24260, v135
	v_cvt_pk_bf16_f32 v132, v132, v133
	v_cvt_pk_bf16_f32 v133, v134, v135
	v_mul_f32_e32 v134, v110, v188
	v_mul_f32_e32 v134, 0xbfb8aa3b, v134
	v_max_f32_e32 v138, 0xda24260, v138
	v_max_f32_e32 v139, 0xda24260, v139
	v_exp_f32_e32 v142, v134
	v_cvt_pk_bf16_f32 v134, v138, v139
	v_max_f32_e32 v140, 0xda24260, v140
	v_max_f32_e32 v141, 0xda24260, v141
	v_cvt_pk_bf16_f32 v135, v140, v141
	global_store_dwordx4 v[136:137], v[132:135], off offset:256
	v_mul_f32_e32 v136, v106, v188
	v_mul_f32_e32 v137, v107, v188
	v_mul_f32_e32 v133, v111, v188
	v_mul_f32_e32 v134, v112, v188
	v_mul_f32_e32 v133, 0xbfb8aa3b, v133
	v_mul_f32_e32 v134, 0xbfb8aa3b, v134
	v_mul_f32_e32 v135, v113, v188
	v_mul_f32_e32 v136, 0xbfb8aa3b, v136
	v_mul_f32_e32 v137, 0xbfb8aa3b, v137
	v_mul_f32_e32 v138, v108, v188
	v_exp_f32_e32 v133, v133
	v_exp_f32_e32 v134, v134
	v_mul_f32_e32 v135, 0xbfb8aa3b, v135
; __device__ __forceinline__ float sigmoidf_(float v) { return __builtin_amdgcn_rcpf(1.f + __builtin_amdgcn_exp2f(-1.4426950408889634f * v)); }
; __device__ __forceinline__ u32x4 pk8(f32x4 a, f32x4 b) { const u32x2 p = pk4(a), q = pk4(b); return (u32x4){p.x, p.y, q.x, q.y}; }
; template <int K>
; __device__ __forceinline__ void epilogue_p(const f32x4 (&acc)[2][2][4][2], const Unit& u, const EpiDesc& E, const Ctx& C, int wr, int wc, int fr, int fq) {
;     ...
;             } else {
;                 const int br = (pn - 10) >> 2, cb = 256 * ((pn - 10) & 3);
; #pragma unroll
;                 for (int ai = 0; ai < 2; ++ai)
; #pragma unroll
;                     for (int m = 0; m < 4; ++m) {
;                         const int row = row0 + 128 * ai + 16 * m;
; #pragma unroll
;                         for (int bj = 0; bj < 2; ++bj) {
;                             f32x4 sg[2];
; #pragma unroll
;                             for (int n = 0; n < 2; ++n) {
;                                 const f32x4 x = acc[ai][bj][m][n] * rstd[ai][m];
; #pragma unroll
;                                 for (int i = 0; i < 4; ++i) sg[n][i] = fmaxf(sigmoidf_(x[i]), 1e-30f);
;                             }
;                             *(u32x4*)(C.G + (size_t)row * 3072 + br * 1024 + cb + 128 * bj + lc8) = pk8(sg[0], sg[1]);
;                         }
;                     }
	v_exp_f32_e32 v136, v136
	v_exp_f32_e32 v137, v137
	v_mul_f32_e32 v138, 0xbfb8aa3b, v138
	v_mul_f32_e32 v139, v109, v188
	v_exp_f32_e32 v135, v135
	v_exp_f32_e32 v138, v138
	v_mul_f32_e32 v139, 0xbfb8aa3b, v139
	v_exp_f32_e32 v139, v139
	v_add_f32_e32 v132, 1.0, v142
	v_add_f32_e32 v133, 1.0, v133
	v_add_f32_e32 v134, 1.0, v134
	v_add_f32_e32 v136, 1.0, v136
	v_add_f32_e32 v137, 1.0, v137
	v_rcp_f32_e32 v132, v132
	v_rcp_f32_e32 v133, v133
	v_rcp_f32_e32 v134, v134
	v_add_f32_e32 v135, 1.0, v135
	v_rcp_f32_e32 v136, v136
	v_rcp_f32_e32 v137, v137
	v_add_f32_e32 v138, 1.0, v138
	v_rcp_f32_e32 v135, v135
	v_rcp_f32_e32 v138, v138
	v_add_f32_e32 v139, 1.0, v139
	v_rcp_f32_e32 v139, v139
	v_max_f32_e32 v132, 0xda24260, v132
	v_max_f32_e32 v133, 0xda24260, v133
	v_max_f32_e32 v134, 0xda24260, v134
	v_max_f32_e32 v136, 0xda24260, v136
	v_max_f32_e32 v137, 0xda24260, v137
	v_max_f32_e32 v135, 0xda24260, v135
	v_max_f32_e32 v138, 0xda24260, v138
	v_cvt_pk_bf16_f32 v132, v132, v133
	v_cvt_pk_bf16_f32 v133, v134, v135
	v_cvt_pk_bf16_f32 v134, v136, v137
	v_mad_i64_i32 v[136:137], s[22:23], v190, s44, v[130:131]
	v_max_f32_e32 v139, 0xda24260, v139
	v_cvt_pk_bf16_f32 v135, v138, v139
	v_lshl_add_u64 v[136:137], v[136:137], 0, s[18:19]
	v_mul_f32_e32 v138, v102, v188
	v_mul_f32_e32 v138, 0xbfb8aa3b, v138
	v_lshl_add_u64 v[136:137], v[136:137], 0, s[2:3]
	v_exp_f32_e32 v138, v138
	v_lshl_add_u64 v[136:137], v[136:137], 0, v[0:1]
	global_store_dwordx4 v[136:137], v[132:135], off
	v_mul_f32_e32 v139, v99, v188
	v_mul_f32_e32 v139, 0xbfb8aa3b, v139
	v_mul_f32_e32 v133, v103, v188
	v_mul_f32_e32 v134, v104, v188
	v_mul_f32_e32 v133, 0xbfb8aa3b, v133
	v_mul_f32_e32 v134, 0xbfb8aa3b, v134
	v_mul_f32_e32 v135, v105, v188
	v_exp_f32_e32 v133, v133
	v_exp_f32_e32 v134, v134
	v_mul_f32_e32 v135, 0xbfb8aa3b, v135
	v_add_f32_e32 v132, 1.0, v138
	v_exp_f32_e32 v135, v135
	v_mul_f32_e32 v138, v98, v188
	v_mul_f32_e32 v138, 0xbfb8aa3b, v138
	v_mul_f32_e32 v140, v100, v188
	v_mul_f32_e32 v141, v101, v188
	v_exp_f32_e32 v138, v138
	v_exp_f32_e32 v139, v139
	v_mul_f32_e32 v140, 0xbfb8aa3b, v140
	v_mul_f32_e32 v141, 0xbfb8aa3b, v141
	v_add_f32_e32 v133, 1.0, v133
	v_add_f32_e32 v134, 1.0, v134
	v_exp_f32_e32 v140, v140
	v_exp_f32_e32 v141, v141
	v_rcp_f32_e32 v132, v132
	v_rcp_f32_e32 v133, v133
	v_rcp_f32_e32 v134, v134
	v_add_f32_e32 v135, 1.0, v135
	v_rcp_f32_e32 v135, v135
	v_add_f32_e32 v138, 1.0, v138
	v_add_f32_e32 v139, 1.0, v139
	v_rcp_f32_e32 v138, v138
	v_rcp_f32_e32 v139, v139
	v_add_f32_e32 v140, 1.0, v140
	v_add_f32_e32 v141, 1.0, v141
	v_max_f32_e32 v132, 0xda24260, v132
	v_max_f32_e32 v133, 0xda24260, v133
	v_max_f32_e32 v134, 0xda24260, v134
	v_rcp_f32_e32 v140, v140
	v_rcp_f32_e32 v141, v141
	v_max_f32_e32 v135, 0xda24260, v135
	v_cvt_pk_bf16_f32 v132, v132, v133
	v_cvt_pk_bf16_f32 v133, v134, v135
	v_mul_f32_e32 v134, v94, v184
	v_mul_f32_e32 v134, 0xbfb8aa3b, v134
	v_max_f32_e32 v138, 0xda24260, v138
	v_max_f32_e32 v139, 0xda24260, v139
	v_exp_f32_e32 v142, v134
	v_cvt_pk_bf16_f32 v134, v138, v139
	v_max_f32_e32 v140, 0xda24260, v140
	v_max_f32_e32 v141, 0xda24260, v141
	v_cvt_pk_bf16_f32 v135, v140, v141
	global_store_dwordx4 v[136:137], v[132:135], off offset:256
	v_mul_f32_e32 v136, v90, v184
	v_mul_f32_e32 v137, v91, v184
	v_mul_f32_e32 v133, v95, v184
	v_mul_f32_e32 v134, v96, v184
	v_mul_f32_e32 v133, 0xbfb8aa3b, v133
	v_mul_f32_e32 v134, 0xbfb8aa3b, v134
	v_mul_f32_e32 v135, v97, v184
	v_mul_f32_e32 v136, 0xbfb8aa3b, v136
	v_mul_f32_e32 v137, 0xbfb8aa3b, v137
	v_mul_f32_e32 v138, v92, v184
	v_exp_f32_e32 v133, v133
	v_exp_f32_e32 v134, v134
	v_mul_f32_e32 v135, 0xbfb8aa3b, v135
	v_exp_f32_e32 v136, v136
	v_exp_f32_e32 v137, v137
	v_mul_f32_e32 v138, 0xbfb8aa3b, v138
	v_mul_f32_e32 v139, v93, v184
	v_exp_f32_e32 v135, v135
	v_exp_f32_e32 v138, v138
	v_mul_f32_e32 v139, 0xbfb8aa3b, v139
	v_exp_f32_e32 v139, v139
	v_add_f32_e32 v132, 1.0, v142
	v_add_f32_e32 v133, 1.0, v133
	v_add_f32_e32 v134, 1.0, v134
	v_add_f32_e32 v136, 1.0, v136
	v_add_f32_e32 v137, 1.0, v137
	v_rcp_f32_e32 v132, v132
	v_rcp_f32_e32 v133, v133
	v_rcp_f32_e32 v134, v134
	v_add_f32_e32 v135, 1.0, v135
	v_rcp_f32_e32 v136, v136
	v_rcp_f32_e32 v137, v137
	v_add_f32_e32 v138, 1.0, v138
	v_rcp_f32_e32 v135, v135
	v_rcp_f32_e32 v138, v138
	v_add_f32_e32 v139, 1.0, v139
	v_rcp_f32_e32 v139, v139
	v_max_f32_e32 v132, 0xda24260, v132
	v_max_f32_e32 v133, 0xda24260, v133
	v_max_f32_e32 v134, 0xda24260, v134
	v_max_f32_e32 v136, 0xda24260, v136
	v_max_f32_e32 v137, 0xda24260, v137
	v_max_f32_e32 v135, 0xda24260, v135
	v_max_f32_e32 v138, 0xda24260, v138
	v_cvt_pk_bf16_f32 v132, v132, v133
	v_cvt_pk_bf16_f32 v133, v134, v135
	v_cvt_pk_bf16_f32 v134, v136, v137
	v_mad_i64_i32 v[136:137], s[22:23], v186, s44, v[130:131]
	v_max_f32_e32 v139, 0xda24260, v139
	v_cvt_pk_bf16_f32 v135, v138, v139
	v_lshl_add_u64 v[136:137], v[136:137], 0, s[18:19]
	v_mul_f32_e32 v138, v86, v184
	v_mul_f32_e32 v138, 0xbfb8aa3b, v138
	v_lshl_add_u64 v[136:137], v[136:137], 0, s[2:3]
	v_exp_f32_e32 v138, v138
	v_lshl_add_u64 v[136:137], v[136:137], 0, v[0:1]
	global_store_dwordx4 v[136:137], v[132:135], off
	v_mul_f32_e32 v139, v83, v184
	v_mul_f32_e32 v139, 0xbfb8aa3b, v139
	v_mul_f32_e32 v133, v87, v184
	v_mul_f32_e32 v134, v88, v184
	v_mul_f32_e32 v133, 0xbfb8aa3b, v133
	v_mul_f32_e32 v134, 0xbfb8aa3b, v134
	v_mul_f32_e32 v135, v89, v184
	v_exp_f32_e32 v133, v133
	v_exp_f32_e32 v134, v134
	v_mul_f32_e32 v135, 0xbfb8aa3b, v135
	v_add_f32_e32 v132, 1.0, v138
	v_exp_f32_e32 v135, v135
	v_mul_f32_e32 v138, v82, v184
	v_mul_f32_e32 v138, 0xbfb8aa3b, v138
	v_mul_f32_e32 v140, v84, v184
	v_mul_f32_e32 v141, v85, v184
; __device__ __forceinline__ float sigmoidf_(float v) { return __builtin_amdgcn_rcpf(1.f + __builtin_amdgcn_exp2f(-1.4426950408889634f * v)); }
; __device__ __forceinline__ u32x4 pk8(f32x4 a, f32x4 b) { const u32x2 p = pk4(a), q = pk4(b); return (u32x4){p.x, p.y, q.x, q.y}; }
; template <int K>
; __device__ __forceinline__ void epilogue_p(const f32x4 (&acc)[2][2][4][2], const Unit& u, const EpiDesc& E, const Ctx& C, int wr, int wc, int fr, int fq) {
;     ...
;             } else {
;                 const int br = (pn - 10) >> 2, cb = 256 * ((pn - 10) & 3);
; #pragma unroll
;                 for (int ai = 0; ai < 2; ++ai)
; #pragma unroll
;                     for (int m = 0; m < 4; ++m) {
;                         const int row = row0 + 128 * ai + 16 * m;
; #pragma unroll
;                         for (int bj = 0; bj < 2; ++bj) {
;                             f32x4 sg[2];
; #pragma unroll
;                             for (int n = 0; n < 2; ++n) {
;                                 const f32x4 x = acc[ai][bj][m][n] * rstd[ai][m];
; #pragma unroll
;                                 for (int i = 0; i < 4; ++i) sg[n][i] = fmaxf(sigmoidf_(x[i]), 1e-30f);
;                             }
;                             *(u32x4*)(C.G + (size_t)row * 3072 + br * 1024 + cb + 128 * bj + lc8) = pk8(sg[0], sg[1]);
;                         }
;                     }
	v_exp_f32_e32 v138, v138
	v_exp_f32_e32 v139, v139
	v_mul_f32_e32 v140, 0xbfb8aa3b, v140
	v_mul_f32_e32 v141, 0xbfb8aa3b, v141
	v_add_f32_e32 v133, 1.0, v133
	v_add_f32_e32 v134, 1.0, v134
	v_exp_f32_e32 v140, v140
	v_exp_f32_e32 v141, v141
	v_rcp_f32_e32 v132, v132
	v_rcp_f32_e32 v133, v133
	v_rcp_f32_e32 v134, v134
	v_add_f32_e32 v135, 1.0, v135
	v_rcp_f32_e32 v135, v135
	v_add_f32_e32 v138, 1.0, v138
	v_add_f32_e32 v139, 1.0, v139
	v_rcp_f32_e32 v138, v138
	v_rcp_f32_e32 v139, v139
	v_add_f32_e32 v140, 1.0, v140
	v_add_f32_e32 v141, 1.0, v141
	v_max_f32_e32 v132, 0xda24260, v132
	v_max_f32_e32 v133, 0xda24260, v133
	v_max_f32_e32 v134, 0xda24260, v134
	v_rcp_f32_e32 v140, v140
	v_rcp_f32_e32 v141, v141
	v_max_f32_e32 v135, 0xda24260, v135
	v_cvt_pk_bf16_f32 v132, v132, v133
	v_cvt_pk_bf16_f32 v133, v134, v135
	v_mul_f32_e32 v134, v78, v162
	v_mul_f32_e32 v134, 0xbfb8aa3b, v134
	v_max_f32_e32 v138, 0xda24260, v138
	v_max_f32_e32 v139, 0xda24260, v139
	v_exp_f32_e32 v142, v134
	v_cvt_pk_bf16_f32 v134, v138, v139
	v_max_f32_e32 v140, 0xda24260, v140
	v_max_f32_e32 v141, 0xda24260, v141
	v_cvt_pk_bf16_f32 v135, v140, v141
	global_store_dwordx4 v[136:137], v[132:135], off offset:256
	v_mul_f32_e32 v136, v74, v162
	v_mul_f32_e32 v137, v75, v162
	v_mul_f32_e32 v133, v79, v162
	v_mul_f32_e32 v134, v80, v162
	v_mul_f32_e32 v133, 0xbfb8aa3b, v133
	v_mul_f32_e32 v134, 0xbfb8aa3b, v134
	v_mul_f32_e32 v135, v81, v162
	v_mul_f32_e32 v136, 0xbfb8aa3b, v136
	v_mul_f32_e32 v137, 0xbfb8aa3b, v137
	v_mul_f32_e32 v138, v76, v162
	v_exp_f32_e32 v133, v133
	v_exp_f32_e32 v134, v134
	v_mul_f32_e32 v135, 0xbfb8aa3b, v135
	v_exp_f32_e32 v136, v136
	v_exp_f32_e32 v137, v137
	v_mul_f32_e32 v138, 0xbfb8aa3b, v138
	v_mul_f32_e32 v139, v77, v162
	v_exp_f32_e32 v135, v135
	v_exp_f32_e32 v138, v138
	v_mul_f32_e32 v139, 0xbfb8aa3b, v139
	v_exp_f32_e32 v139, v139
	v_add_f32_e32 v132, 1.0, v142
	v_add_f32_e32 v133, 1.0, v133
	v_add_f32_e32 v134, 1.0, v134
	v_add_f32_e32 v136, 1.0, v136
	v_add_f32_e32 v137, 1.0, v137
	v_rcp_f32_e32 v132, v132
	v_rcp_f32_e32 v133, v133
	v_rcp_f32_e32 v134, v134
	v_add_f32_e32 v135, 1.0, v135
	v_rcp_f32_e32 v136, v136
	v_rcp_f32_e32 v137, v137
	v_add_f32_e32 v138, 1.0, v138
	v_rcp_f32_e32 v135, v135
	v_rcp_f32_e32 v138, v138
	v_add_f32_e32 v139, 1.0, v139
	v_rcp_f32_e32 v139, v139
	v_max_f32_e32 v132, 0xda24260, v132
	v_max_f32_e32 v133, 0xda24260, v133
	v_max_f32_e32 v134, 0xda24260, v134
	v_max_f32_e32 v136, 0xda24260, v136
	v_max_f32_e32 v137, 0xda24260, v137
	v_max_f32_e32 v135, 0xda24260, v135
	v_max_f32_e32 v138, 0xda24260, v138
	v_cvt_pk_bf16_f32 v132, v132, v133
	v_cvt_pk_bf16_f32 v133, v134, v135
	v_cvt_pk_bf16_f32 v134, v136, v137
	v_mad_i64_i32 v[136:137], s[22:23], v164, s44, v[130:131]
	v_max_f32_e32 v139, 0xda24260, v139
	v_cvt_pk_bf16_f32 v135, v138, v139
	v_lshl_add_u64 v[136:137], v[136:137], 0, s[18:19]
	v_mul_f32_e32 v138, v70, v162
	v_mul_f32_e32 v138, 0xbfb8aa3b, v138
	v_lshl_add_u64 v[136:137], v[136:137], 0, s[2:3]
	v_exp_f32_e32 v138, v138
	v_lshl_add_u64 v[136:137], v[136:137], 0, v[0:1]
	global_store_dwordx4 v[136:137], v[132:135], off
	v_mul_f32_e32 v139, v67, v162
	v_mul_f32_e32 v139, 0xbfb8aa3b, v139
	v_mul_f32_e32 v133, v71, v162
	v_mul_f32_e32 v134, v72, v162
	v_mul_f32_e32 v133, 0xbfb8aa3b, v133
	v_mul_f32_e32 v134, 0xbfb8aa3b, v134
	v_mul_f32_e32 v135, v73, v162
	v_exp_f32_e32 v133, v133
	v_exp_f32_e32 v134, v134
	v_mul_f32_e32 v135, 0xbfb8aa3b, v135
	v_add_f32_e32 v132, 1.0, v138
	v_exp_f32_e32 v135, v135
	v_mul_f32_e32 v138, v66, v162
	v_mul_f32_e32 v138, 0xbfb8aa3b, v138
	v_mul_f32_e32 v140, v68, v162
	v_mul_f32_e32 v141, v69, v162
	v_exp_f32_e32 v138, v138
	v_exp_f32_e32 v139, v139
	v_mul_f32_e32 v140, 0xbfb8aa3b, v140
	v_mul_f32_e32 v141, 0xbfb8aa3b, v141
	v_add_f32_e32 v133, 1.0, v133
	v_add_f32_e32 v134, 1.0, v134
	v_exp_f32_e32 v140, v140
	v_exp_f32_e32 v141, v141
	v_rcp_f32_e32 v132, v132
	v_rcp_f32_e32 v133, v133
	v_rcp_f32_e32 v134, v134
	v_add_f32_e32 v135, 1.0, v135
	v_rcp_f32_e32 v135, v135
	v_add_f32_e32 v138, 1.0, v138
	v_add_f32_e32 v139, 1.0, v139
	v_rcp_f32_e32 v138, v138
	v_rcp_f32_e32 v139, v139
	v_add_f32_e32 v140, 1.0, v140
	v_add_f32_e32 v141, 1.0, v141
	v_max_f32_e32 v132, 0xda24260, v132
	v_max_f32_e32 v133, 0xda24260, v133
	v_max_f32_e32 v134, 0xda24260, v134
	v_rcp_f32_e32 v140, v140
	v_rcp_f32_e32 v141, v141
	v_max_f32_e32 v135, 0xda24260, v135
	v_cvt_pk_bf16_f32 v132, v132, v133
	v_cvt_pk_bf16_f32 v133, v134, v135
	v_mul_f32_e32 v134, v62, v158
	v_mul_f32_e32 v134, 0xbfb8aa3b, v134
	v_max_f32_e32 v138, 0xda24260, v138
	v_max_f32_e32 v139, 0xda24260, v139
	v_exp_f32_e32 v142, v134
	v_cvt_pk_bf16_f32 v134, v138, v139
	v_max_f32_e32 v140, 0xda24260, v140
	v_max_f32_e32 v141, 0xda24260, v141
	v_cvt_pk_bf16_f32 v135, v140, v141
	global_store_dwordx4 v[136:137], v[132:135], off offset:256
	v_mul_f32_e32 v136, v58, v158
	v_mul_f32_e32 v137, v59, v158
	v_mul_f32_e32 v133, v63, v158
	v_mul_f32_e32 v134, v64, v158
	v_mul_f32_e32 v133, 0xbfb8aa3b, v133
	v_mul_f32_e32 v134, 0xbfb8aa3b, v134
	v_mul_f32_e32 v135, v65, v158
	v_mul_f32_e32 v136, 0xbfb8aa3b, v136
	v_mul_f32_e32 v137, 0xbfb8aa3b, v137
	v_mul_f32_e32 v138, v60, v158
	v_exp_f32_e32 v133, v133
	v_exp_f32_e32 v134, v134
	v_mul_f32_e32 v135, 0xbfb8aa3b, v135
	v_exp_f32_e32 v136, v136
	v_exp_f32_e32 v137, v137
	v_mul_f32_e32 v138, 0xbfb8aa3b, v138
	v_mul_f32_e32 v139, v61, v158
	v_exp_f32_e32 v135, v135
	v_exp_f32_e32 v138, v138
	v_mul_f32_e32 v139, 0xbfb8aa3b, v139
	v_exp_f32_e32 v139, v139
	v_add_f32_e32 v132, 1.0, v142
	v_add_f32_e32 v133, 1.0, v133
	v_add_f32_e32 v134, 1.0, v134
	v_add_f32_e32 v136, 1.0, v136
	v_add_f32_e32 v137, 1.0, v137
; __device__ __forceinline__ float sigmoidf_(float v) { return __builtin_amdgcn_rcpf(1.f + __builtin_amdgcn_exp2f(-1.4426950408889634f * v)); }
; __device__ __forceinline__ u32x4 pk8(f32x4 a, f32x4 b) { const u32x2 p = pk4(a), q = pk4(b); return (u32x4){p.x, p.y, q.x, q.y}; }
; template <int K>
; __device__ __forceinline__ void epilogue_p(const f32x4 (&acc)[2][2][4][2], const Unit& u, const EpiDesc& E, const Ctx& C, int wr, int wc, int fr, int fq) {
;     ...
;             } else {
;                 const int br = (pn - 10) >> 2, cb = 256 * ((pn - 10) & 3);
; #pragma unroll
;                 for (int ai = 0; ai < 2; ++ai)
; #pragma unroll
;                     for (int m = 0; m < 4; ++m) {
;                         const int row = row0 + 128 * ai + 16 * m;
; #pragma unroll
;                         for (int bj = 0; bj < 2; ++bj) {
;                             f32x4 sg[2];
; #pragma unroll
;                             for (int n = 0; n < 2; ++n) {
;                                 const f32x4 x = acc[ai][bj][m][n] * rstd[ai][m];
; #pragma unroll
;                                 for (int i = 0; i < 4; ++i) sg[n][i] = fmaxf(sigmoidf_(x[i]), 1e-30f);
;                             }
;                             *(u32x4*)(C.G + (size_t)row * 3072 + br * 1024 + cb + 128 * bj + lc8) = pk8(sg[0], sg[1]);
;                         }
;                     }
	v_rcp_f32_e32 v132, v132
	v_rcp_f32_e32 v133, v133
	v_rcp_f32_e32 v134, v134
	v_add_f32_e32 v135, 1.0, v135
	v_rcp_f32_e32 v136, v136
	v_rcp_f32_e32 v137, v137
	v_add_f32_e32 v138, 1.0, v138
	v_rcp_f32_e32 v135, v135
	v_rcp_f32_e32 v138, v138
	v_add_f32_e32 v139, 1.0, v139
	v_rcp_f32_e32 v139, v139
	v_max_f32_e32 v132, 0xda24260, v132
	v_max_f32_e32 v133, 0xda24260, v133
	v_max_f32_e32 v134, 0xda24260, v134
	v_max_f32_e32 v136, 0xda24260, v136
	v_max_f32_e32 v137, 0xda24260, v137
	v_max_f32_e32 v135, 0xda24260, v135
	v_max_f32_e32 v138, 0xda24260, v138
	v_cvt_pk_bf16_f32 v132, v132, v133
	v_cvt_pk_bf16_f32 v133, v134, v135
	v_cvt_pk_bf16_f32 v134, v136, v137
	v_mad_i64_i32 v[136:137], s[22:23], v160, s44, v[130:131]
	v_max_f32_e32 v139, 0xda24260, v139
	v_cvt_pk_bf16_f32 v135, v138, v139
	v_lshl_add_u64 v[136:137], v[136:137], 0, s[18:19]
	v_mul_f32_e32 v138, v54, v158
	v_mul_f32_e32 v138, 0xbfb8aa3b, v138
	v_lshl_add_u64 v[136:137], v[136:137], 0, s[2:3]
	v_exp_f32_e32 v138, v138
	v_lshl_add_u64 v[136:137], v[136:137], 0, v[0:1]
	global_store_dwordx4 v[136:137], v[132:135], off
	v_mul_f32_e32 v139, v51, v158
	v_mul_f32_e32 v139, 0xbfb8aa3b, v139
	v_mul_f32_e32 v133, v55, v158
	v_mul_f32_e32 v134, v56, v158
	v_mul_f32_e32 v133, 0xbfb8aa3b, v133
	v_mul_f32_e32 v134, 0xbfb8aa3b, v134
	v_mul_f32_e32 v135, v57, v158
	v_exp_f32_e32 v133, v133
	v_exp_f32_e32 v134, v134
	v_mul_f32_e32 v135, 0xbfb8aa3b, v135
	v_add_f32_e32 v132, 1.0, v138
	v_exp_f32_e32 v135, v135
	v_mul_f32_e32 v138, v50, v158
	v_mul_f32_e32 v138, 0xbfb8aa3b, v138
	v_mul_f32_e32 v140, v52, v158
	v_mul_f32_e32 v141, v53, v158
	v_exp_f32_e32 v138, v138
	v_exp_f32_e32 v139, v139
	v_mul_f32_e32 v140, 0xbfb8aa3b, v140
	v_mul_f32_e32 v141, 0xbfb8aa3b, v141
	v_add_f32_e32 v133, 1.0, v133
	v_add_f32_e32 v134, 1.0, v134
	v_exp_f32_e32 v140, v140
	v_exp_f32_e32 v141, v141
	v_rcp_f32_e32 v132, v132
	v_rcp_f32_e32 v133, v133
	v_rcp_f32_e32 v134, v134
	v_add_f32_e32 v135, 1.0, v135
	v_rcp_f32_e32 v135, v135
	v_add_f32_e32 v138, 1.0, v138
	v_add_f32_e32 v139, 1.0, v139
	v_rcp_f32_e32 v138, v138
	v_rcp_f32_e32 v139, v139
	v_add_f32_e32 v140, 1.0, v140
	v_add_f32_e32 v141, 1.0, v141
	v_max_f32_e32 v132, 0xda24260, v132
	v_max_f32_e32 v133, 0xda24260, v133
	v_max_f32_e32 v134, 0xda24260, v134
	v_rcp_f32_e32 v140, v140
	v_rcp_f32_e32 v141, v141
	v_max_f32_e32 v135, 0xda24260, v135
	v_cvt_pk_bf16_f32 v132, v132, v133
	v_cvt_pk_bf16_f32 v133, v134, v135
	v_mul_f32_e32 v134, v46, v154
	v_mul_f32_e32 v134, 0xbfb8aa3b, v134
	v_max_f32_e32 v138, 0xda24260, v138
	v_max_f32_e32 v139, 0xda24260, v139
	v_exp_f32_e32 v142, v134
	v_cvt_pk_bf16_f32 v134, v138, v139
	v_max_f32_e32 v140, 0xda24260, v140
	v_max_f32_e32 v141, 0xda24260, v141
	v_cvt_pk_bf16_f32 v135, v140, v141
	global_store_dwordx4 v[136:137], v[132:135], off offset:256
	v_mul_f32_e32 v136, v42, v154
	v_mul_f32_e32 v137, v43, v154
	v_mul_f32_e32 v133, v47, v154
	v_mul_f32_e32 v134, v48, v154
	v_mul_f32_e32 v133, 0xbfb8aa3b, v133
	v_mul_f32_e32 v134, 0xbfb8aa3b, v134
	v_mul_f32_e32 v135, v49, v154
	v_mul_f32_e32 v136, 0xbfb8aa3b, v136
	v_mul_f32_e32 v137, 0xbfb8aa3b, v137
	v_mul_f32_e32 v138, v44, v154
	v_exp_f32_e32 v133, v133
	v_exp_f32_e32 v134, v134
	v_mul_f32_e32 v135, 0xbfb8aa3b, v135
	v_exp_f32_e32 v136, v136
	v_exp_f32_e32 v137, v137
	v_mul_f32_e32 v138, 0xbfb8aa3b, v138
	v_mul_f32_e32 v139, v45, v154
	v_exp_f32_e32 v135, v135
	v_exp_f32_e32 v138, v138
	v_mul_f32_e32 v139, 0xbfb8aa3b, v139
	v_exp_f32_e32 v139, v139
	v_add_f32_e32 v132, 1.0, v142
	v_add_f32_e32 v133, 1.0, v133
	v_add_f32_e32 v134, 1.0, v134
	v_add_f32_e32 v136, 1.0, v136
	v_add_f32_e32 v137, 1.0, v137
	v_rcp_f32_e32 v132, v132
	v_rcp_f32_e32 v133, v133
	v_rcp_f32_e32 v134, v134
	v_add_f32_e32 v135, 1.0, v135
	v_rcp_f32_e32 v136, v136
	v_rcp_f32_e32 v137, v137
	v_add_f32_e32 v138, 1.0, v138
	v_rcp_f32_e32 v135, v135
	v_rcp_f32_e32 v138, v138
	v_add_f32_e32 v139, 1.0, v139
	v_rcp_f32_e32 v139, v139
	v_max_f32_e32 v132, 0xda24260, v132
	v_max_f32_e32 v133, 0xda24260, v133
	v_max_f32_e32 v134, 0xda24260, v134
	v_max_f32_e32 v136, 0xda24260, v136
	v_max_f32_e32 v137, 0xda24260, v137
	v_max_f32_e32 v135, 0xda24260, v135
	v_max_f32_e32 v138, 0xda24260, v138
	v_cvt_pk_bf16_f32 v132, v132, v133
	v_cvt_pk_bf16_f32 v133, v134, v135
	v_cvt_pk_bf16_f32 v134, v136, v137
	v_mad_i64_i32 v[136:137], s[22:23], v156, s44, v[130:131]
	v_max_f32_e32 v139, 0xda24260, v139
	v_cvt_pk_bf16_f32 v135, v138, v139
	v_lshl_add_u64 v[136:137], v[136:137], 0, s[18:19]
	v_mul_f32_e32 v138, v38, v154
	v_mul_f32_e32 v138, 0xbfb8aa3b, v138
	v_lshl_add_u64 v[136:137], v[136:137], 0, s[2:3]
	v_exp_f32_e32 v138, v138
	v_lshl_add_u64 v[136:137], v[136:137], 0, v[0:1]
	global_store_dwordx4 v[136:137], v[132:135], off
	v_mul_f32_e32 v139, v35, v154
	v_mul_f32_e32 v139, 0xbfb8aa3b, v139
	v_mul_f32_e32 v133, v39, v154
	v_mul_f32_e32 v134, v40, v154
	v_mul_f32_e32 v133, 0xbfb8aa3b, v133
	v_mul_f32_e32 v134, 0xbfb8aa3b, v134
	v_mul_f32_e32 v135, v41, v154
	v_exp_f32_e32 v133, v133
	v_exp_f32_e32 v134, v134
	v_mul_f32_e32 v135, 0xbfb8aa3b, v135
	v_add_f32_e32 v132, 1.0, v138
	v_exp_f32_e32 v135, v135
	v_mul_f32_e32 v138, v34, v154
	v_mul_f32_e32 v138, 0xbfb8aa3b, v138
	v_mul_f32_e32 v140, v36, v154
	v_mul_f32_e32 v141, v37, v154
	v_exp_f32_e32 v138, v138
	v_exp_f32_e32 v139, v139
	v_mul_f32_e32 v140, 0xbfb8aa3b, v140
	v_mul_f32_e32 v141, 0xbfb8aa3b, v141
	v_add_f32_e32 v133, 1.0, v133
	v_add_f32_e32 v134, 1.0, v134
	v_exp_f32_e32 v140, v140
	v_exp_f32_e32 v141, v141
	v_rcp_f32_e32 v132, v132
	v_rcp_f32_e32 v133, v133
	v_rcp_f32_e32 v134, v134
	v_add_f32_e32 v135, 1.0, v135
	v_rcp_f32_e32 v135, v135
	v_add_f32_e32 v138, 1.0, v138
; __device__ __forceinline__ float sigmoidf_(float v) { return __builtin_amdgcn_rcpf(1.f + __builtin_amdgcn_exp2f(-1.4426950408889634f * v)); }
; __device__ __forceinline__ u32x4 pk8(f32x4 a, f32x4 b) { const u32x2 p = pk4(a), q = pk4(b); return (u32x4){p.x, p.y, q.x, q.y}; }
; template <int K>
; __device__ __forceinline__ void epilogue_p(const f32x4 (&acc)[2][2][4][2], const Unit& u, const EpiDesc& E, const Ctx& C, int wr, int wc, int fr, int fq) {
;     ...
;             } else {
;                 const int br = (pn - 10) >> 2, cb = 256 * ((pn - 10) & 3);
; #pragma unroll
;                 for (int ai = 0; ai < 2; ++ai)
; #pragma unroll
;                     for (int m = 0; m < 4; ++m) {
;                         const int row = row0 + 128 * ai + 16 * m;
; #pragma unroll
;                         for (int bj = 0; bj < 2; ++bj) {
;                             f32x4 sg[2];
; #pragma unroll
;                             for (int n = 0; n < 2; ++n) {
;                                 const f32x4 x = acc[ai][bj][m][n] * rstd[ai][m];
; #pragma unroll
;                                 for (int i = 0; i < 4; ++i) sg[n][i] = fmaxf(sigmoidf_(x[i]), 1e-30f);
;                             }
;                             *(u32x4*)(C.G + (size_t)row * 3072 + br * 1024 + cb + 128 * bj + lc8) = pk8(sg[0], sg[1]);
;                         }
;                     }
	v_add_f32_e32 v139, 1.0, v139
	v_rcp_f32_e32 v138, v138
	v_rcp_f32_e32 v139, v139
	v_add_f32_e32 v140, 1.0, v140
	v_add_f32_e32 v141, 1.0, v141
	v_max_f32_e32 v132, 0xda24260, v132
	v_max_f32_e32 v133, 0xda24260, v133
	v_max_f32_e32 v134, 0xda24260, v134
	v_rcp_f32_e32 v140, v140
	v_rcp_f32_e32 v141, v141
	v_max_f32_e32 v135, 0xda24260, v135
	v_cvt_pk_bf16_f32 v132, v132, v133
	v_cvt_pk_bf16_f32 v133, v134, v135
	v_mul_f32_e32 v134, v30, v150
	v_mul_f32_e32 v134, 0xbfb8aa3b, v134
	v_max_f32_e32 v138, 0xda24260, v138
	v_max_f32_e32 v139, 0xda24260, v139
	v_exp_f32_e32 v142, v134
	v_cvt_pk_bf16_f32 v134, v138, v139
	v_max_f32_e32 v140, 0xda24260, v140
	v_max_f32_e32 v141, 0xda24260, v141
	v_cvt_pk_bf16_f32 v135, v140, v141
	global_store_dwordx4 v[136:137], v[132:135], off offset:256
	v_mul_f32_e32 v136, v26, v150
	v_mul_f32_e32 v137, v27, v150
	v_mul_f32_e32 v133, v31, v150
	v_mul_f32_e32 v134, v32, v150
	v_mul_f32_e32 v133, 0xbfb8aa3b, v133
	v_mul_f32_e32 v134, 0xbfb8aa3b, v134
	v_mul_f32_e32 v135, v33, v150
	v_mul_f32_e32 v136, 0xbfb8aa3b, v136
	v_mul_f32_e32 v137, 0xbfb8aa3b, v137
	v_mul_f32_e32 v138, v28, v150
	v_exp_f32_e32 v133, v133
	v_exp_f32_e32 v134, v134
	v_mul_f32_e32 v135, 0xbfb8aa3b, v135
	v_exp_f32_e32 v136, v136
	v_exp_f32_e32 v137, v137
	v_mul_f32_e32 v138, 0xbfb8aa3b, v138
	v_mul_f32_e32 v139, v29, v150
	v_exp_f32_e32 v135, v135
	v_exp_f32_e32 v138, v138
	v_mul_f32_e32 v139, 0xbfb8aa3b, v139
	v_exp_f32_e32 v139, v139
	v_add_f32_e32 v132, 1.0, v142
	v_add_f32_e32 v133, 1.0, v133
	v_add_f32_e32 v134, 1.0, v134
	v_add_f32_e32 v136, 1.0, v136
	v_add_f32_e32 v137, 1.0, v137
	v_rcp_f32_e32 v132, v132
	v_rcp_f32_e32 v133, v133
	v_rcp_f32_e32 v134, v134
	v_add_f32_e32 v135, 1.0, v135
	v_rcp_f32_e32 v136, v136
	v_rcp_f32_e32 v137, v137
	v_add_f32_e32 v138, 1.0, v138
	v_rcp_f32_e32 v135, v135
	v_rcp_f32_e32 v138, v138
	v_add_f32_e32 v139, 1.0, v139
	v_rcp_f32_e32 v139, v139
	v_max_f32_e32 v132, 0xda24260, v132
	v_max_f32_e32 v133, 0xda24260, v133
	v_max_f32_e32 v134, 0xda24260, v134
	v_max_f32_e32 v136, 0xda24260, v136
	v_max_f32_e32 v137, 0xda24260, v137
	v_max_f32_e32 v135, 0xda24260, v135
	v_max_f32_e32 v138, 0xda24260, v138
	v_cvt_pk_bf16_f32 v132, v132, v133
	v_cvt_pk_bf16_f32 v133, v134, v135
	v_cvt_pk_bf16_f32 v134, v136, v137
	v_mad_i64_i32 v[136:137], s[22:23], v152, s44, v[130:131]
	v_max_f32_e32 v139, 0xda24260, v139
	v_cvt_pk_bf16_f32 v135, v138, v139
	v_lshl_add_u64 v[136:137], v[136:137], 0, s[18:19]
	v_mul_f32_e32 v138, v22, v150
	v_mul_f32_e32 v138, 0xbfb8aa3b, v138
	v_lshl_add_u64 v[136:137], v[136:137], 0, s[2:3]
	v_exp_f32_e32 v138, v138
	v_lshl_add_u64 v[136:137], v[136:137], 0, v[0:1]
	global_store_dwordx4 v[136:137], v[132:135], off
	v_mul_f32_e32 v139, v19, v150
	v_mul_f32_e32 v139, 0xbfb8aa3b, v139
	v_mul_f32_e32 v133, v23, v150
	v_mul_f32_e32 v134, v24, v150
	v_mul_f32_e32 v133, 0xbfb8aa3b, v133
	v_mul_f32_e32 v134, 0xbfb8aa3b, v134
	v_mul_f32_e32 v135, v25, v150
	v_exp_f32_e32 v133, v133
	v_exp_f32_e32 v134, v134
	v_mul_f32_e32 v135, 0xbfb8aa3b, v135
	v_add_f32_e32 v132, 1.0, v138
	v_exp_f32_e32 v135, v135
	v_mul_f32_e32 v138, v18, v150
	v_mul_f32_e32 v138, 0xbfb8aa3b, v138
	v_mul_f32_e32 v140, v20, v150
	v_mul_f32_e32 v141, v21, v150
	v_exp_f32_e32 v138, v138
	v_exp_f32_e32 v139, v139
	v_mul_f32_e32 v140, 0xbfb8aa3b, v140
	v_mul_f32_e32 v141, 0xbfb8aa3b, v141
	v_add_f32_e32 v133, 1.0, v133
	v_add_f32_e32 v134, 1.0, v134
	v_exp_f32_e32 v140, v140
	v_exp_f32_e32 v141, v141
	v_rcp_f32_e32 v132, v132
	v_rcp_f32_e32 v133, v133
	v_rcp_f32_e32 v134, v134
	v_add_f32_e32 v135, 1.0, v135
	v_rcp_f32_e32 v135, v135
	v_add_f32_e32 v138, 1.0, v138
	v_add_f32_e32 v139, 1.0, v139
	v_rcp_f32_e32 v138, v138
	v_rcp_f32_e32 v139, v139
	v_add_f32_e32 v140, 1.0, v140
	v_add_f32_e32 v141, 1.0, v141
	v_max_f32_e32 v132, 0xda24260, v132
	v_max_f32_e32 v133, 0xda24260, v133
	v_max_f32_e32 v134, 0xda24260, v134
	v_rcp_f32_e32 v140, v140
	v_rcp_f32_e32 v141, v141
	v_max_f32_e32 v135, 0xda24260, v135
; __device__ __forceinline__ float sigmoidf_(float v) { return __builtin_amdgcn_rcpf(1.f + __builtin_amdgcn_exp2f(-1.4426950408889634f * v)); }
; __device__ __forceinline__ u32x4 pk8(f32x4 a, f32x4 b) { const u32x2 p = pk4(a), q = pk4(b); return (u32x4){p.x, p.y, q.x, q.y}; }
; template <int K>
; __device__ __forceinline__ void epilogue_p(const f32x4 (&acc)[2][2][4][2], const Unit& u, const EpiDesc& E, const Ctx& C, int wr, int wc, int fr, int fq) {
;     ...
;             } else {
;                 const int br = (pn - 10) >> 2, cb = 256 * ((pn - 10) & 3);
; #pragma unroll
;                 for (int ai = 0; ai < 2; ++ai)
; #pragma unroll
;                     for (int m = 0; m < 4; ++m) {
;                         const int row = row0 + 128 * ai + 16 * m;
; #pragma unroll
;                         for (int bj = 0; bj < 2; ++bj) {
;                             f32x4 sg[2];
; #pragma unroll
;                             for (int n = 0; n < 2; ++n) {
;                                 const f32x4 x = acc[ai][bj][m][n] * rstd[ai][m];
; #pragma unroll
;                                 for (int i = 0; i < 4; ++i) sg[n][i] = fmaxf(sigmoidf_(x[i]), 1e-30f);
;                             }
;                             *(u32x4*)(C.G + (size_t)row * 3072 + br * 1024 + cb + 128 * bj + lc8) = pk8(sg[0], sg[1]);
;                         }
;                     }
	v_cvt_pk_bf16_f32 v132, v132, v133
	v_cvt_pk_bf16_f32 v133, v134, v135
	v_mul_f32_e32 v134, v14, v146
	v_mul_f32_e32 v134, 0xbfb8aa3b, v134
	v_max_f32_e32 v138, 0xda24260, v138
	v_max_f32_e32 v139, 0xda24260, v139
	v_exp_f32_e32 v142, v134
	v_cvt_pk_bf16_f32 v134, v138, v139
	v_max_f32_e32 v140, 0xda24260, v140
	v_max_f32_e32 v141, 0xda24260, v141
	v_cvt_pk_bf16_f32 v135, v140, v141
	global_store_dwordx4 v[136:137], v[132:135], off offset:256
	v_mul_f32_e32 v136, v10, v146
	v_mul_f32_e32 v136, 0xbfb8aa3b, v136
	v_mul_f32_e32 v133, v15, v146
	v_mul_f32_e32 v134, v16, v146
	v_mul_f32_e32 v133, 0xbfb8aa3b, v133
	v_mul_f32_e32 v134, 0xbfb8aa3b, v134
	v_mul_f32_e32 v135, v17, v146
	v_mul_f32_e32 v137, v11, v146
	v_exp_f32_e32 v133, v133
	v_exp_f32_e32 v134, v134
	v_mul_f32_e32 v135, 0xbfb8aa3b, v135
	v_exp_f32_e32 v136, v136
	v_mul_f32_e32 v137, 0xbfb8aa3b, v137
	v_mul_f32_e32 v138, v12, v146
	v_exp_f32_e32 v135, v135
	v_exp_f32_e32 v137, v137
	v_mul_f32_e32 v138, 0xbfb8aa3b, v138
	v_mul_f32_e32 v139, v13, v146
	v_exp_f32_e32 v138, v138
	v_mul_f32_e32 v139, 0xbfb8aa3b, v139
	v_exp_f32_e32 v139, v139
	v_add_f32_e32 v132, 1.0, v142
	v_add_f32_e32 v133, 1.0, v133
	v_add_f32_e32 v134, 1.0, v134
	v_add_f32_e32 v136, 1.0, v136
	v_rcp_f32_e32 v132, v132
	v_rcp_f32_e32 v133, v133
	v_rcp_f32_e32 v134, v134
	v_add_f32_e32 v135, 1.0, v135
	v_rcp_f32_e32 v136, v136
	v_add_f32_e32 v137, 1.0, v137
	v_rcp_f32_e32 v135, v135
	v_rcp_f32_e32 v137, v137
	v_add_f32_e32 v138, 1.0, v138
	v_rcp_f32_e32 v138, v138
	v_add_f32_e32 v139, 1.0, v139
	v_rcp_f32_e32 v139, v139
	v_max_f32_e32 v132, 0xda24260, v132
	v_max_f32_e32 v133, 0xda24260, v133
	v_max_f32_e32 v134, 0xda24260, v134
	v_max_f32_e32 v136, 0xda24260, v136
	v_max_f32_e32 v135, 0xda24260, v135
	v_max_f32_e32 v137, 0xda24260, v137
	v_cvt_pk_bf16_f32 v132, v132, v133
	v_cvt_pk_bf16_f32 v133, v134, v135
	v_cvt_pk_bf16_f32 v134, v136, v137
	v_mul_f32_e32 v136, v6, v146
	v_max_f32_e32 v138, 0xda24260, v138
	v_mad_i64_i32 v[130:131], s[22:23], v148, s44, v[130:131]
	v_mul_f32_e32 v136, 0xbfb8aa3b, v136
	v_max_f32_e32 v139, 0xda24260, v139
	v_cvt_pk_bf16_f32 v135, v138, v139
	v_lshl_add_u64 v[130:131], v[130:131], 0, s[18:19]
	v_exp_f32_e32 v138, v136
	v_lshl_add_u64 v[130:131], v[130:131], 0, s[2:3]
	v_lshl_add_u64 v[136:137], v[130:131], 0, v[0:1]
	global_store_dwordx4 v[136:137], v[132:135], off
	v_mul_f32_e32 v130, v7, v146
	v_mul_f32_e32 v131, v8, v146
	v_mul_f32_e32 v132, v9, v146
	v_mul_f32_e32 v133, v2, v146
	v_add_f32_e32 v0, 1.0, v138
	v_mul_f32_e32 v130, 0xbfb8aa3b, v130
	v_mul_f32_e32 v131, 0xbfb8aa3b, v131
	v_mul_f32_e32 v132, 0xbfb8aa3b, v132
	v_mul_f32_e32 v133, 0xbfb8aa3b, v133
	v_mul_f32_e32 v134, v3, v146
	v_mul_f32_e32 v135, v4, v146
	v_mul_f32_e32 v138, v5, v146
	v_exp_f32_e32 v130, v130
	v_exp_f32_e32 v131, v131
	v_exp_f32_e32 v132, v132
	v_exp_f32_e32 v133, v133
	v_mul_f32_e32 v134, 0xbfb8aa3b, v134
	v_mul_f32_e32 v135, 0xbfb8aa3b, v135
	v_mul_f32_e32 v138, 0xbfb8aa3b, v138
	v_exp_f32_e32 v134, v134
	v_exp_f32_e32 v135, v135
	v_exp_f32_e32 v138, v138
	v_add_f32_e32 v130, 1.0, v130
	v_add_f32_e32 v131, 1.0, v131
	v_add_f32_e32 v132, 1.0, v132
	v_add_f32_e32 v133, 1.0, v133
	v_rcp_f32_e32 v130, v130
	v_rcp_f32_e32 v131, v131
	v_rcp_f32_e32 v132, v132
	v_rcp_f32_e32 v133, v133
	v_add_f32_e32 v134, 1.0, v134
	v_add_f32_e32 v135, 1.0, v135
	v_add_f32_e32 v138, 1.0, v138
	v_rcp_f32_e32 v0, v0
	v_rcp_f32_e32 v134, v134
	v_rcp_f32_e32 v135, v135
	v_rcp_f32_e32 v138, v138
	v_max_f32_e32 v130, 0xda24260, v130
	v_max_f32_e32 v131, 0xda24260, v131
	v_max_f32_e32 v132, 0xda24260, v132
	v_max_f32_e32 v133, 0xda24260, v133
	v_max_f32_e32 v0, 0xda24260, v0
	v_max_f32_e32 v134, 0xda24260, v134
	v_max_f32_e32 v135, 0xda24260, v135
	v_max_f32_e32 v138, 0xda24260, v138
	v_cvt_pk_bf16_f32 v130, v0, v130
	v_cvt_pk_bf16_f32 v131, v131, v132
	v_cvt_pk_bf16_f32 v132, v133, v134
	v_cvt_pk_bf16_f32 v133, v135, v138
	global_store_dwordx4 v[136:137], v[130:133], off offset:256
	s_mov_b64 s[2:3], 0
